# MLP_UP phases: workgroups start staggered in 4 groups (0-4us) so the 32MB hid store bursts of the unit epilogues do not coincide
# speedup vs baseline: 1.0442x; 1.0045x over previous
.LBB0_820:
	s_cmp_lt_i32 s74, 8
	s_cselect_b64 s[0:1], -1, 0
	s_and_b64 s[4:5], s[0:1], s[4:5]
	s_andn2_b64 vcc, exec, s[4:5]
	s_cbranch_vccnz .LBB0_856
	s_bitcmp1_b32 s2, 3
	s_cbranch_scc0 .Lstag_u0_a
	s_sleep 40
.Lstag_u0_a:
	s_bitcmp1_b32 s2, 4
	s_cbranch_scc0 .Lstag_u0_b
	s_sleep 80
.Lstag_u0_b:
	s_abs_i32 s3, s34
	v_cvt_f32_u32_e32 v0, s3
	s_add_i32 s4, s34, 0x7ff
	s_sub_i32 s5, 0xfffff801, s34
	s_xor_b32 s6, s4, s34
	v_rcp_iflag_f32_e32 v0, v0
	s_max_i32 s4, s4, s5
	s_sub_i32 s5, 0, s3
	s_ashr_i32 s6, s6, 31
	v_mul_f32_e32 v0, 0x4f7ffffe, v0
	v_cvt_u32_f32_e32 v0, v0
	s_waitcnt lgkmcnt(0)
	v_readfirstlane_b32 s17, v192
	v_readfirstlane_b32 s7, v0
	s_mul_i32 s5, s5, s7
	s_mul_hi_u32 s5, s7, s5
	s_add_i32 s7, s7, s5
	s_mul_hi_u32 s5, s4, s7
	s_mul_i32 s7, s5, s3
	s_sub_i32 s4, s4, s7
	s_add_i32 s8, s5, 1
	s_sub_i32 s7, s4, s3
	s_cmp_ge_u32 s4, s3
	s_cselect_b32 s5, s8, s5
	s_cselect_b32 s4, s7, s4
	s_add_i32 s7, s5, 1
	s_cmp_ge_u32 s4, s3
	s_cselect_b32 s3, s7, s5
	s_xor_b32 s3, s3, s6
	s_sub_i32 s3, s3, s6
	s_cmp_lt_i32 s3, 1
	s_cselect_b64 s[4:5], -1, 0
	s_cmpk_gt_i32 s2, 0x7ff
	s_cselect_b64 s[6:7], -1, 0
	s_or_b64 s[4:5], s[6:7], s[4:5]
	s_and_b64 vcc, exec, s[4:5]
	s_cbranch_vccnz .LBB0_856
	s_ashr_i32 s50, s2, 31
	s_lshr_b32 s4, s50, 29
	s_add_i32 s7, s2, s4
	s_and_b32 s4, s7, -8
	s_sub_i32 s8, s2, s4
	s_cmp_gt_i32 s8, -1
	s_cbranch_scc0 .LBB0_824
	s_lshl_b32 s6, s8, 8
	s_cbranch_execz .LBB0_825
	s_branch .LBB0_826

.LBB0_1266:
	s_cmp_lt_i32 s74, 13
	s_cselect_b64 s[0:1], -1, 0
	s_and_b64 s[4:5], s[0:1], s[4:5]
	s_andn2_b64 vcc, exec, s[4:5]
	s_cbranch_vccnz .LBB0_1302
	s_bitcmp1_b32 s2, 3
	s_cbranch_scc0 .Lstag_u1_a
	s_sleep 40

.Lstag_u1_b:
	s_abs_i32 s3, s34
	v_cvt_f32_u32_e32 v0, s3
	s_add_i32 s4, s34, 0x7ff
	s_sub_i32 s5, 0xfffff801, s34
	s_xor_b32 s6, s4, s34
	v_rcp_iflag_f32_e32 v0, v0
	s_max_i32 s4, s4, s5
	s_sub_i32 s5, 0, s3
	s_ashr_i32 s6, s6, 31
	v_mul_f32_e32 v0, 0x4f7ffffe, v0
	v_cvt_u32_f32_e32 v0, v0
	v_readfirstlane_b32 s19, v192
	v_readfirstlane_b32 s7, v0
	s_mul_i32 s5, s5, s7
	s_mul_hi_u32 s5, s7, s5
	s_add_i32 s7, s7, s5
	s_mul_hi_u32 s5, s4, s7
	s_mul_i32 s7, s5, s3
	s_sub_i32 s4, s4, s7
	s_add_i32 s8, s5, 1
	s_sub_i32 s7, s4, s3
	s_cmp_ge_u32 s4, s3
	s_cselect_b32 s5, s8, s5
	s_cselect_b32 s4, s7, s4
	s_add_i32 s7, s5, 1
	s_cmp_ge_u32 s4, s3
	s_cselect_b32 s3, s7, s5
	s_xor_b32 s3, s3, s6
	s_sub_i32 s3, s3, s6
	s_cmp_lt_i32 s3, 1
	s_cselect_b64 s[4:5], -1, 0
	s_cmpk_gt_i32 s2, 0x7ff
	s_cselect_b64 s[6:7], -1, 0
	s_or_b64 s[4:5], s[6:7], s[4:5]
	s_and_b64 vcc, exec, s[4:5]
	s_cbranch_vccnz .LBB0_1302
	s_ashr_i32 s52, s2, 31
	s_lshr_b32 s4, s52, 29
	s_add_i32 s7, s2, s4
	s_and_b32 s4, s7, -8
	s_sub_i32 s8, s2, s4
	s_cmp_gt_i32 s8, -1
	s_cbranch_scc0 .LBB0_1270
	s_lshl_b32 s6, s8, 8
	s_cbranch_execz .LBB0_1271
	s_branch .LBB0_1272
